# RESID epilogue: nt (streaming) hint on the 128 residual-stream ushort loads
# speedup vs baseline: 1.0076x; 1.0009x over previous
; DI float bf2f(u16 v) { return __uint_as_float(((unsigned)v) << 16); }
; DI int crow(int i, int h) { return (i & 3) + 8 * (i >> 2) + 4 * h; }
; DI void phase_gemm_resid(const Params& p, const u16* A, int lda, int K, const u16* Bt, bool last_sub, float scl,
;                          int row0, int nrows, char* smem) {
;     ...
;   auto epi = [&](int xcd, int q, f32x16 (&acc)[4][2]) __attribute__((always_inline)) {
;     G256_EPI_IDS
;     const int mt = xcd * mpx + (q >> 5) * 8 + (q & 7), nt = (q >> 3) & 3;
; #pragma unroll
;     for (int ms = 0; ms < 4; ++ms)
; #pragma unroll
;       for (int ns = 0; ns < 2; ++ns)
; #pragma unroll
;         for (int i = 0; i < 16; ++i) {
;           const size_t row = (size_t)row0 + mt * 256 + wm * 128 + ms * 32 + crow(i, lh);
;           const int col = nt * 256 + wn * 64 + ns * 32 + lr;
;           __builtin_nontemporal_store(__builtin_bit_cast(u16, (_Float16)(ALPHA * bf2f(xres[row * D + col]) + scl * acc[ms][ns][i])), &r16[row * D + col]);
;         }
;   };
.LBB0_842:
	s_lshr_b32 s6, s48, 2
	s_and_b32 s7, s48, 7
	s_waitcnt vmcnt(1)
	v_mov_b32_e32 v132, v196
	s_and_b32 s6, s6, 8
	s_or_b32 s7, s7, s42
	s_waitcnt lgkmcnt(0)
	s_barrier
	s_add_i32 s7, s7, s6
	s_lshl_b32 s6, s7, 8
	s_add_i32 s62, s6, s37
	s_lshl_b32 s6, s48, 5
	s_and_b32 s6, s6, 0x300
	v_mfma_f32_32x32x16_bf16 v[18:33], v[134:137], v[150:153], v[18:33]
	v_mfma_f32_32x32x16_bf16 v[2:17], v[134:137], v[154:157], v[2:17]
	v_mfma_f32_32x32x16_bf16 v[114:129], v[158:161], v[150:153], v[114:129]
	v_mfma_f32_32x32x16_bf16 v[50:65], v[138:141], v[150:153], v[50:65]
	v_mfma_f32_32x32x16_bf16 v[34:49], v[138:141], v[154:157], v[34:49]
	v_mfma_f32_32x32x16_bf16 v[82:97], v[146:149], v[150:153], v[82:97]
	v_mfma_f32_32x32x16_bf16 v[66:81], v[146:149], v[154:157], v[66:81]
	v_mfma_f32_32x32x16_bf16 v[98:113], v[158:161], v[154:157], v[98:113]
	s_mov_b64 s[8:9], -1
	s_and_b64 vcc, exec, s[0:1]
	v_lshrrev_b32_e32 v163, 1, v196
	v_and_b32_e32 v163, 0xffffff80, v163
	v_lshrrev_b32_e32 v164, 3, v196
	v_and_b32_e32 v164, 4, v164
	v_add3_u32 v163, v163, v164, s62
	v_and_b32_e32 v164, 0xdf, v196
	v_or_b32_e32 v164, s6, v164
	v_lshl_add_u32 v162, v163, 10, v164
	v_lshlrev_b32_e32 v162, 1, v162
	s_add_u32 s98, s14, 0x1000
	s_addc_u32 s99, s15, 0
	s_add_u32 s100, s12, 0x1000
	s_addc_u32 s101, s13, 0
	global_load_ushort v130, v162, s[98:99] offset:-4096 nt
	global_load_ushort v131, v162, s[98:99] offset:-4032 nt
	global_load_ushort v132, v162, s[98:99] offset:-2048 nt
	global_load_ushort v133, v162, s[98:99] offset:-1984 nt
	global_load_ushort v134, v162, s[98:99] offset:0 nt
	global_load_ushort v135, v162, s[98:99] offset:64 nt
	global_load_ushort v136, v162, s[98:99] offset:2048 nt
	global_load_ushort v137, v162, s[98:99] offset:2112 nt
	s_add_u32 s98, s98, 0x4000
	s_addc_u32 s99, s99, 0
	global_load_ushort v138, v162, s[98:99] offset:-4096 nt
	global_load_ushort v139, v162, s[98:99] offset:-4032 nt
	global_load_ushort v140, v162, s[98:99] offset:-2048 nt
	global_load_ushort v141, v162, s[98:99] offset:-1984 nt
	global_load_ushort v142, v162, s[98:99] offset:0 nt
	global_load_ushort v143, v162, s[98:99] offset:64 nt
	global_load_ushort v144, v162, s[98:99] offset:2048 nt
	global_load_ushort v145, v162, s[98:99] offset:2112 nt
	s_add_u32 s98, s98, 0x4000
	s_addc_u32 s99, s99, 0
	global_load_ushort v146, v162, s[98:99] offset:-4096 nt
	global_load_ushort v147, v162, s[98:99] offset:-4032 nt
	global_load_ushort v148, v162, s[98:99] offset:-2048 nt
	global_load_ushort v149, v162, s[98:99] offset:-1984 nt
	global_load_ushort v150, v162, s[98:99] offset:0 nt
	global_load_ushort v151, v162, s[98:99] offset:64 nt
	global_load_ushort v152, v162, s[98:99] offset:2048 nt
	global_load_ushort v153, v162, s[98:99] offset:2112 nt
	s_add_u32 s98, s98, 0x4000
	s_addc_u32 s99, s99, 0
	global_load_ushort v154, v162, s[98:99] offset:-4096 nt
	global_load_ushort v155, v162, s[98:99] offset:-4032 nt
	global_load_ushort v156, v162, s[98:99] offset:-2048 nt
	global_load_ushort v157, v162, s[98:99] offset:-1984 nt
	global_load_ushort v158, v162, s[98:99] offset:0 nt
	global_load_ushort v159, v162, s[98:99] offset:64 nt
	global_load_ushort v160, v162, s[98:99] offset:2048 nt
	global_load_ushort v161, v162, s[98:99] offset:2112 nt
	s_add_u32 s98, s98, 0x4000
	s_addc_u32 s99, s99, 0
	s_waitcnt vmcnt(16)
	v_lshlrev_b32_e32 v130, 16, v130
	v_mul_f32_e32 v130, 0x3fb504f3, v130
	v_fma_mixlo_f16 v130, s36, v114, v130
	global_store_short v162, v130, s[100:101] offset:-4096 nt
	v_lshlrev_b32_e32 v131, 16, v131
	v_mul_f32_e32 v131, 0x3fb504f3, v131
	v_fma_mixlo_f16 v131, s36, v98, v131
	global_store_short v162, v131, s[100:101] offset:-4032 nt
	v_lshlrev_b32_e32 v132, 16, v132
	v_mul_f32_e32 v132, 0x3fb504f3, v132
	v_fma_mixlo_f16 v132, s36, v115, v132
	global_store_short v162, v132, s[100:101] offset:-2048 nt
	v_lshlrev_b32_e32 v133, 16, v133
	v_mul_f32_e32 v133, 0x3fb504f3, v133
	v_fma_mixlo_f16 v133, s36, v99, v133
	global_store_short v162, v133, s[100:101] offset:-1984 nt
	v_lshlrev_b32_e32 v134, 16, v134
	v_mul_f32_e32 v134, 0x3fb504f3, v134
	v_fma_mixlo_f16 v134, s36, v116, v134
	global_store_short v162, v134, s[100:101] offset:0 nt
	v_lshlrev_b32_e32 v135, 16, v135
	v_mul_f32_e32 v135, 0x3fb504f3, v135
	v_fma_mixlo_f16 v135, s36, v100, v135
	global_store_short v162, v135, s[100:101] offset:64 nt
	v_lshlrev_b32_e32 v136, 16, v136
	v_mul_f32_e32 v136, 0x3fb504f3, v136
	v_fma_mixlo_f16 v136, s36, v117, v136
	global_store_short v162, v136, s[100:101] offset:2048 nt
	v_lshlrev_b32_e32 v137, 16, v137
	v_mul_f32_e32 v137, 0x3fb504f3, v137
	v_fma_mixlo_f16 v137, s36, v101, v137
	global_store_short v162, v137, s[100:101] offset:2112 nt
	s_add_u32 s100, s100, 0x4000
	s_addc_u32 s101, s101, 0
	v_lshlrev_b32_e32 v138, 16, v138
	v_mul_f32_e32 v138, 0x3fb504f3, v138
	v_fma_mixlo_f16 v138, s36, v118, v138
	global_store_short v162, v138, s[100:101] offset:-4096 nt
	v_lshlrev_b32_e32 v139, 16, v139
	v_mul_f32_e32 v139, 0x3fb504f3, v139
	v_fma_mixlo_f16 v139, s36, v102, v139
	global_store_short v162, v139, s[100:101] offset:-4032 nt
	v_lshlrev_b32_e32 v140, 16, v140
	v_mul_f32_e32 v140, 0x3fb504f3, v140
	v_fma_mixlo_f16 v140, s36, v119, v140
	global_store_short v162, v140, s[100:101] offset:-2048 nt
	v_lshlrev_b32_e32 v141, 16, v141
	v_mul_f32_e32 v141, 0x3fb504f3, v141
	v_fma_mixlo_f16 v141, s36, v103, v141
	global_store_short v162, v141, s[100:101] offset:-1984 nt
	v_lshlrev_b32_e32 v142, 16, v142
	v_mul_f32_e32 v142, 0x3fb504f3, v142
	v_fma_mixlo_f16 v142, s36, v120, v142
	global_store_short v162, v142, s[100:101] offset:0 nt
	v_lshlrev_b32_e32 v143, 16, v143
	v_mul_f32_e32 v143, 0x3fb504f3, v143
; DI float bf2f(u16 v) { return __uint_as_float(((unsigned)v) << 16); }
; DI int crow(int i, int h) { return (i & 3) + 8 * (i >> 2) + 4 * h; }
; DI void phase_gemm_resid(const Params& p, const u16* A, int lda, int K, const u16* Bt, bool last_sub, float scl,
;                          int row0, int nrows, char* smem) {
;     ...
;         for (int i = 0; i < 16; ++i) {
;           const size_t row = (size_t)row0 + mt * 256 + wm * 128 + ms * 32 + crow(i, lh);
;           const int col = nt * 256 + wn * 64 + ns * 32 + lr;
;           __builtin_nontemporal_store(__builtin_bit_cast(u16, (_Float16)(ALPHA * bf2f(xres[row * D + col]) + scl * acc[ms][ns][i])), &r16[row * D + col]);
;         }
	v_fma_mixlo_f16 v143, s36, v104, v143
	global_store_short v162, v143, s[100:101] offset:64 nt
	v_lshlrev_b32_e32 v144, 16, v144
	v_mul_f32_e32 v144, 0x3fb504f3, v144
	v_fma_mixlo_f16 v144, s36, v121, v144
	global_store_short v162, v144, s[100:101] offset:2048 nt
	v_lshlrev_b32_e32 v145, 16, v145
	v_mul_f32_e32 v145, 0x3fb504f3, v145
	v_fma_mixlo_f16 v145, s36, v105, v145
	global_store_short v162, v145, s[100:101] offset:2112 nt
	s_add_u32 s100, s100, 0x4000
	s_addc_u32 s101, s101, 0
	global_load_ushort v130, v162, s[98:99] offset:-4096 nt
	global_load_ushort v131, v162, s[98:99] offset:-4032 nt
	global_load_ushort v132, v162, s[98:99] offset:-2048 nt
	global_load_ushort v133, v162, s[98:99] offset:-1984 nt
	global_load_ushort v134, v162, s[98:99] offset:0 nt
	global_load_ushort v135, v162, s[98:99] offset:64 nt
	global_load_ushort v136, v162, s[98:99] offset:2048 nt
	global_load_ushort v137, v162, s[98:99] offset:2112 nt
	s_add_u32 s98, s98, 0x4000
	s_addc_u32 s99, s99, 0
	global_load_ushort v138, v162, s[98:99] offset:-4096 nt
	global_load_ushort v139, v162, s[98:99] offset:-4032 nt
	global_load_ushort v140, v162, s[98:99] offset:-2048 nt
	global_load_ushort v141, v162, s[98:99] offset:-1984 nt
	global_load_ushort v142, v162, s[98:99] offset:0 nt
	global_load_ushort v143, v162, s[98:99] offset:64 nt
	global_load_ushort v144, v162, s[98:99] offset:2048 nt
	global_load_ushort v145, v162, s[98:99] offset:2112 nt
	s_add_u32 s98, s98, 0x4000
	s_addc_u32 s99, s99, 0
	s_waitcnt vmcnt(32)
	v_lshlrev_b32_e32 v146, 16, v146
	v_mul_f32_e32 v146, 0x3fb504f3, v146
	v_fma_mixlo_f16 v146, s36, v122, v146
	global_store_short v162, v146, s[100:101] offset:-4096 nt
	v_lshlrev_b32_e32 v147, 16, v147
	v_mul_f32_e32 v147, 0x3fb504f3, v147
	v_fma_mixlo_f16 v147, s36, v106, v147
	global_store_short v162, v147, s[100:101] offset:-4032 nt
	v_lshlrev_b32_e32 v148, 16, v148
	v_mul_f32_e32 v148, 0x3fb504f3, v148
	v_fma_mixlo_f16 v148, s36, v123, v148
	global_store_short v162, v148, s[100:101] offset:-2048 nt
	v_lshlrev_b32_e32 v149, 16, v149
	v_mul_f32_e32 v149, 0x3fb504f3, v149
	v_fma_mixlo_f16 v149, s36, v107, v149
	global_store_short v162, v149, s[100:101] offset:-1984 nt
	v_lshlrev_b32_e32 v150, 16, v150
	v_mul_f32_e32 v150, 0x3fb504f3, v150
	v_fma_mixlo_f16 v150, s36, v124, v150
	global_store_short v162, v150, s[100:101] offset:0 nt
	v_lshlrev_b32_e32 v151, 16, v151
	v_mul_f32_e32 v151, 0x3fb504f3, v151
	v_fma_mixlo_f16 v151, s36, v108, v151
	global_store_short v162, v151, s[100:101] offset:64 nt
	v_lshlrev_b32_e32 v152, 16, v152
	v_mul_f32_e32 v152, 0x3fb504f3, v152
	v_fma_mixlo_f16 v152, s36, v125, v152
	global_store_short v162, v152, s[100:101] offset:2048 nt
	v_lshlrev_b32_e32 v153, 16, v153
	v_mul_f32_e32 v153, 0x3fb504f3, v153
	v_fma_mixlo_f16 v153, s36, v109, v153
	global_store_short v162, v153, s[100:101] offset:2112 nt
	s_add_u32 s100, s100, 0x4000
	s_addc_u32 s101, s101, 0
	v_lshlrev_b32_e32 v154, 16, v154
	v_mul_f32_e32 v154, 0x3fb504f3, v154
	v_fma_mixlo_f16 v154, s36, v126, v154
	global_store_short v162, v154, s[100:101] offset:-4096 nt
	v_lshlrev_b32_e32 v155, 16, v155
	v_mul_f32_e32 v155, 0x3fb504f3, v155
	v_fma_mixlo_f16 v155, s36, v110, v155
	global_store_short v162, v155, s[100:101] offset:-4032 nt
	v_lshlrev_b32_e32 v156, 16, v156
	v_mul_f32_e32 v156, 0x3fb504f3, v156
	v_fma_mixlo_f16 v156, s36, v127, v156
	global_store_short v162, v156, s[100:101] offset:-2048 nt
	v_lshlrev_b32_e32 v157, 16, v157
	v_mul_f32_e32 v157, 0x3fb504f3, v157
	v_fma_mixlo_f16 v157, s36, v111, v157
	global_store_short v162, v157, s[100:101] offset:-1984 nt
	v_lshlrev_b32_e32 v158, 16, v158
	v_mul_f32_e32 v158, 0x3fb504f3, v158
	v_fma_mixlo_f16 v158, s36, v128, v158
	global_store_short v162, v158, s[100:101] offset:0 nt
	v_lshlrev_b32_e32 v159, 16, v159
	v_mul_f32_e32 v159, 0x3fb504f3, v159
	v_fma_mixlo_f16 v159, s36, v112, v159
	global_store_short v162, v159, s[100:101] offset:64 nt
	v_lshlrev_b32_e32 v160, 16, v160
	v_mul_f32_e32 v160, 0x3fb504f3, v160
	v_fma_mixlo_f16 v160, s36, v129, v160
	global_store_short v162, v160, s[100:101] offset:2048 nt
	v_lshlrev_b32_e32 v161, 16, v161
	v_mul_f32_e32 v161, 0x3fb504f3, v161
	v_fma_mixlo_f16 v161, s36, v113, v161
	global_store_short v162, v161, s[100:101] offset:2112 nt
	s_add_u32 s100, s100, 0x4000
	s_addc_u32 s101, s101, 0
	global_load_ushort v146, v162, s[98:99] offset:-4096 nt
	global_load_ushort v147, v162, s[98:99] offset:-4032 nt
	global_load_ushort v148, v162, s[98:99] offset:-2048 nt
	global_load_ushort v149, v162, s[98:99] offset:-1984 nt
	global_load_ushort v150, v162, s[98:99] offset:0 nt
	global_load_ushort v151, v162, s[98:99] offset:64 nt
	global_load_ushort v152, v162, s[98:99] offset:2048 nt
	global_load_ushort v153, v162, s[98:99] offset:2112 nt
	s_add_u32 s98, s98, 0x4000
	s_addc_u32 s99, s99, 0
	global_load_ushort v154, v162, s[98:99] offset:-4096 nt
	global_load_ushort v155, v162, s[98:99] offset:-4032 nt
	global_load_ushort v156, v162, s[98:99] offset:-2048 nt
	global_load_ushort v157, v162, s[98:99] offset:-1984 nt
	global_load_ushort v158, v162, s[98:99] offset:0 nt
	global_load_ushort v159, v162, s[98:99] offset:64 nt
	global_load_ushort v160, v162, s[98:99] offset:2048 nt
	global_load_ushort v161, v162, s[98:99] offset:2112 nt
	s_add_u32 s98, s98, 0x4000
	s_addc_u32 s99, s99, 0
	s_waitcnt vmcnt(32)
; DI float bf2f(u16 v) { return __uint_as_float(((unsigned)v) << 16); }
; DI int crow(int i, int h) { return (i & 3) + 8 * (i >> 2) + 4 * h; }
; DI void phase_gemm_resid(const Params& p, const u16* A, int lda, int K, const u16* Bt, bool last_sub, float scl,
;                          int row0, int nrows, char* smem) {
;     ...
;         for (int i = 0; i < 16; ++i) {
;           const size_t row = (size_t)row0 + mt * 256 + wm * 128 + ms * 32 + crow(i, lh);
;           const int col = nt * 256 + wn * 64 + ns * 32 + lr;
;           __builtin_nontemporal_store(__builtin_bit_cast(u16, (_Float16)(ALPHA * bf2f(xres[row * D + col]) + scl * acc[ms][ns][i])), &r16[row * D + col]);
;         }
	v_lshlrev_b32_e32 v130, 16, v130
	v_mul_f32_e32 v130, 0x3fb504f3, v130
	v_fma_mixlo_f16 v130, s36, v82, v130
	global_store_short v162, v130, s[100:101] offset:-4096 nt
	v_lshlrev_b32_e32 v131, 16, v131
	v_mul_f32_e32 v131, 0x3fb504f3, v131
	v_fma_mixlo_f16 v131, s36, v66, v131
	global_store_short v162, v131, s[100:101] offset:-4032 nt
	v_lshlrev_b32_e32 v132, 16, v132
	v_mul_f32_e32 v132, 0x3fb504f3, v132
	v_fma_mixlo_f16 v132, s36, v83, v132
	global_store_short v162, v132, s[100:101] offset:-2048 nt
	v_lshlrev_b32_e32 v133, 16, v133
	v_mul_f32_e32 v133, 0x3fb504f3, v133
	v_fma_mixlo_f16 v133, s36, v67, v133
	global_store_short v162, v133, s[100:101] offset:-1984 nt
	v_lshlrev_b32_e32 v134, 16, v134
	v_mul_f32_e32 v134, 0x3fb504f3, v134
	v_fma_mixlo_f16 v134, s36, v84, v134
	global_store_short v162, v134, s[100:101] offset:0 nt
	v_lshlrev_b32_e32 v135, 16, v135
	v_mul_f32_e32 v135, 0x3fb504f3, v135
	v_fma_mixlo_f16 v135, s36, v68, v135
	global_store_short v162, v135, s[100:101] offset:64 nt
	v_lshlrev_b32_e32 v136, 16, v136
	v_mul_f32_e32 v136, 0x3fb504f3, v136
	v_fma_mixlo_f16 v136, s36, v85, v136
	global_store_short v162, v136, s[100:101] offset:2048 nt
	v_lshlrev_b32_e32 v137, 16, v137
	v_mul_f32_e32 v137, 0x3fb504f3, v137
	v_fma_mixlo_f16 v137, s36, v69, v137
	global_store_short v162, v137, s[100:101] offset:2112 nt
	s_add_u32 s100, s100, 0x4000
	s_addc_u32 s101, s101, 0
	v_lshlrev_b32_e32 v138, 16, v138
	v_mul_f32_e32 v138, 0x3fb504f3, v138
	v_fma_mixlo_f16 v138, s36, v86, v138
	global_store_short v162, v138, s[100:101] offset:-4096 nt
	v_lshlrev_b32_e32 v139, 16, v139
	v_mul_f32_e32 v139, 0x3fb504f3, v139
	v_fma_mixlo_f16 v139, s36, v70, v139
	global_store_short v162, v139, s[100:101] offset:-4032 nt
	v_lshlrev_b32_e32 v140, 16, v140
	v_mul_f32_e32 v140, 0x3fb504f3, v140
	v_fma_mixlo_f16 v140, s36, v87, v140
	global_store_short v162, v140, s[100:101] offset:-2048 nt
	v_lshlrev_b32_e32 v141, 16, v141
	v_mul_f32_e32 v141, 0x3fb504f3, v141
	v_fma_mixlo_f16 v141, s36, v71, v141
	global_store_short v162, v141, s[100:101] offset:-1984 nt
	v_lshlrev_b32_e32 v142, 16, v142
	v_mul_f32_e32 v142, 0x3fb504f3, v142
	v_fma_mixlo_f16 v142, s36, v88, v142
	global_store_short v162, v142, s[100:101] offset:0 nt
	v_lshlrev_b32_e32 v143, 16, v143
	v_mul_f32_e32 v143, 0x3fb504f3, v143
	v_fma_mixlo_f16 v143, s36, v72, v143
	global_store_short v162, v143, s[100:101] offset:64 nt
	v_lshlrev_b32_e32 v144, 16, v144
	v_mul_f32_e32 v144, 0x3fb504f3, v144
	v_fma_mixlo_f16 v144, s36, v89, v144
	global_store_short v162, v144, s[100:101] offset:2048 nt
	v_lshlrev_b32_e32 v145, 16, v145
	v_mul_f32_e32 v145, 0x3fb504f3, v145
	v_fma_mixlo_f16 v145, s36, v73, v145
	global_store_short v162, v145, s[100:101] offset:2112 nt
	s_add_u32 s100, s100, 0x4000
	s_addc_u32 s101, s101, 0
	global_load_ushort v130, v162, s[98:99] offset:-4096 nt
	global_load_ushort v131, v162, s[98:99] offset:-4032 nt
	global_load_ushort v132, v162, s[98:99] offset:-2048 nt
	global_load_ushort v133, v162, s[98:99] offset:-1984 nt
	global_load_ushort v134, v162, s[98:99] offset:0 nt
	global_load_ushort v135, v162, s[98:99] offset:64 nt
	global_load_ushort v136, v162, s[98:99] offset:2048 nt
	global_load_ushort v137, v162, s[98:99] offset:2112 nt
	s_add_u32 s98, s98, 0x4000
	s_addc_u32 s99, s99, 0
	global_load_ushort v138, v162, s[98:99] offset:-4096 nt
	global_load_ushort v139, v162, s[98:99] offset:-4032 nt
	global_load_ushort v140, v162, s[98:99] offset:-2048 nt
	global_load_ushort v141, v162, s[98:99] offset:-1984 nt
	global_load_ushort v142, v162, s[98:99] offset:0 nt
	global_load_ushort v143, v162, s[98:99] offset:64 nt
	global_load_ushort v144, v162, s[98:99] offset:2048 nt
	global_load_ushort v145, v162, s[98:99] offset:2112 nt
	s_add_u32 s98, s98, 0x4000
	s_addc_u32 s99, s99, 0
	s_waitcnt vmcnt(32)
	v_lshlrev_b32_e32 v146, 16, v146
	v_mul_f32_e32 v146, 0x3fb504f3, v146
	v_fma_mixlo_f16 v146, s36, v90, v146
	global_store_short v162, v146, s[100:101] offset:-4096 nt
	v_lshlrev_b32_e32 v147, 16, v147
	v_mul_f32_e32 v147, 0x3fb504f3, v147
	v_fma_mixlo_f16 v147, s36, v74, v147
	global_store_short v162, v147, s[100:101] offset:-4032 nt
	v_lshlrev_b32_e32 v148, 16, v148
	v_mul_f32_e32 v148, 0x3fb504f3, v148
	v_fma_mixlo_f16 v148, s36, v91, v148
	global_store_short v162, v148, s[100:101] offset:-2048 nt
	v_lshlrev_b32_e32 v149, 16, v149
	v_mul_f32_e32 v149, 0x3fb504f3, v149
	v_fma_mixlo_f16 v149, s36, v75, v149
	global_store_short v162, v149, s[100:101] offset:-1984 nt
	v_lshlrev_b32_e32 v150, 16, v150
	v_mul_f32_e32 v150, 0x3fb504f3, v150
	v_fma_mixlo_f16 v150, s36, v92, v150
	global_store_short v162, v150, s[100:101] offset:0 nt
	v_lshlrev_b32_e32 v151, 16, v151
	v_mul_f32_e32 v151, 0x3fb504f3, v151
	v_fma_mixlo_f16 v151, s36, v76, v151
	global_store_short v162, v151, s[100:101] offset:64 nt
	v_lshlrev_b32_e32 v152, 16, v152
	v_mul_f32_e32 v152, 0x3fb504f3, v152
	v_fma_mixlo_f16 v152, s36, v93, v152
	global_store_short v162, v152, s[100:101] offset:2048 nt
	v_lshlrev_b32_e32 v153, 16, v153
	v_mul_f32_e32 v153, 0x3fb504f3, v153
	v_fma_mixlo_f16 v153, s36, v77, v153
	global_store_short v162, v153, s[100:101] offset:2112 nt
	s_add_u32 s100, s100, 0x4000
	s_addc_u32 s101, s101, 0
	v_lshlrev_b32_e32 v154, 16, v154
	v_mul_f32_e32 v154, 0x3fb504f3, v154
	v_fma_mixlo_f16 v154, s36, v94, v154
	global_store_short v162, v154, s[100:101] offset:-4096 nt
	v_lshlrev_b32_e32 v155, 16, v155
	v_mul_f32_e32 v155, 0x3fb504f3, v155
	v_fma_mixlo_f16 v155, s36, v78, v155
	global_store_short v162, v155, s[100:101] offset:-4032 nt
	v_lshlrev_b32_e32 v156, 16, v156
	v_mul_f32_e32 v156, 0x3fb504f3, v156
; DI float bf2f(u16 v) { return __uint_as_float(((unsigned)v) << 16); }
; DI int crow(int i, int h) { return (i & 3) + 8 * (i >> 2) + 4 * h; }
; DI void phase_gemm_resid(const Params& p, const u16* A, int lda, int K, const u16* Bt, bool last_sub, float scl,
;                          int row0, int nrows, char* smem) {
;     ...
;         for (int i = 0; i < 16; ++i) {
;           const size_t row = (size_t)row0 + mt * 256 + wm * 128 + ms * 32 + crow(i, lh);
;           const int col = nt * 256 + wn * 64 + ns * 32 + lr;
;           __builtin_nontemporal_store(__builtin_bit_cast(u16, (_Float16)(ALPHA * bf2f(xres[row * D + col]) + scl * acc[ms][ns][i])), &r16[row * D + col]);
;         }
	v_fma_mixlo_f16 v156, s36, v95, v156
	global_store_short v162, v156, s[100:101] offset:-2048 nt
	v_lshlrev_b32_e32 v157, 16, v157
	v_mul_f32_e32 v157, 0x3fb504f3, v157
	v_fma_mixlo_f16 v157, s36, v79, v157
	global_store_short v162, v157, s[100:101] offset:-1984 nt
	v_lshlrev_b32_e32 v158, 16, v158
	v_mul_f32_e32 v158, 0x3fb504f3, v158
	v_fma_mixlo_f16 v158, s36, v96, v158
	global_store_short v162, v158, s[100:101] offset:0 nt
	v_lshlrev_b32_e32 v159, 16, v159
	v_mul_f32_e32 v159, 0x3fb504f3, v159
	v_fma_mixlo_f16 v159, s36, v80, v159
	global_store_short v162, v159, s[100:101] offset:64 nt
	v_lshlrev_b32_e32 v160, 16, v160
	v_mul_f32_e32 v160, 0x3fb504f3, v160
	v_fma_mixlo_f16 v160, s36, v97, v160
	global_store_short v162, v160, s[100:101] offset:2048 nt
	v_lshlrev_b32_e32 v161, 16, v161
	v_mul_f32_e32 v161, 0x3fb504f3, v161
	v_fma_mixlo_f16 v161, s36, v81, v161
	global_store_short v162, v161, s[100:101] offset:2112 nt
	s_add_u32 s100, s100, 0x4000
	s_addc_u32 s101, s101, 0
	global_load_ushort v146, v162, s[98:99] offset:-4096 nt
	global_load_ushort v147, v162, s[98:99] offset:-4032 nt
	global_load_ushort v148, v162, s[98:99] offset:-2048 nt
	global_load_ushort v149, v162, s[98:99] offset:-1984 nt
	global_load_ushort v150, v162, s[98:99] offset:0 nt
	global_load_ushort v151, v162, s[98:99] offset:64 nt
	global_load_ushort v152, v162, s[98:99] offset:2048 nt
	global_load_ushort v153, v162, s[98:99] offset:2112 nt
	s_add_u32 s98, s98, 0x4000
	s_addc_u32 s99, s99, 0
	global_load_ushort v154, v162, s[98:99] offset:-4096 nt
	global_load_ushort v155, v162, s[98:99] offset:-4032 nt
	global_load_ushort v156, v162, s[98:99] offset:-2048 nt
	global_load_ushort v157, v162, s[98:99] offset:-1984 nt
	global_load_ushort v158, v162, s[98:99] offset:0 nt
	global_load_ushort v159, v162, s[98:99] offset:64 nt
	global_load_ushort v160, v162, s[98:99] offset:2048 nt
	global_load_ushort v161, v162, s[98:99] offset:2112 nt
	s_add_u32 s98, s98, 0x4000
	s_addc_u32 s99, s99, 0
	s_waitcnt vmcnt(32)
	v_lshlrev_b32_e32 v130, 16, v130
	v_mul_f32_e32 v130, 0x3fb504f3, v130
	v_fma_mixlo_f16 v130, s36, v50, v130
	global_store_short v162, v130, s[100:101] offset:-4096 nt
	v_lshlrev_b32_e32 v131, 16, v131
	v_mul_f32_e32 v131, 0x3fb504f3, v131
	v_fma_mixlo_f16 v131, s36, v34, v131
	global_store_short v162, v131, s[100:101] offset:-4032 nt
	v_lshlrev_b32_e32 v132, 16, v132
	v_mul_f32_e32 v132, 0x3fb504f3, v132
	v_fma_mixlo_f16 v132, s36, v51, v132
	global_store_short v162, v132, s[100:101] offset:-2048 nt
	v_lshlrev_b32_e32 v133, 16, v133
	v_mul_f32_e32 v133, 0x3fb504f3, v133
	v_fma_mixlo_f16 v133, s36, v35, v133
	global_store_short v162, v133, s[100:101] offset:-1984 nt
	v_lshlrev_b32_e32 v134, 16, v134
	v_mul_f32_e32 v134, 0x3fb504f3, v134
	v_fma_mixlo_f16 v134, s36, v52, v134
	global_store_short v162, v134, s[100:101] offset:0 nt
	v_lshlrev_b32_e32 v135, 16, v135
	v_mul_f32_e32 v135, 0x3fb504f3, v135
	v_fma_mixlo_f16 v135, s36, v36, v135
	global_store_short v162, v135, s[100:101] offset:64 nt
	v_lshlrev_b32_e32 v136, 16, v136
	v_mul_f32_e32 v136, 0x3fb504f3, v136
	v_fma_mixlo_f16 v136, s36, v53, v136
	global_store_short v162, v136, s[100:101] offset:2048 nt
	v_lshlrev_b32_e32 v137, 16, v137
	v_mul_f32_e32 v137, 0x3fb504f3, v137
	v_fma_mixlo_f16 v137, s36, v37, v137
	global_store_short v162, v137, s[100:101] offset:2112 nt
	s_add_u32 s100, s100, 0x4000
	s_addc_u32 s101, s101, 0
	v_lshlrev_b32_e32 v138, 16, v138
	v_mul_f32_e32 v138, 0x3fb504f3, v138
	v_fma_mixlo_f16 v138, s36, v54, v138
	global_store_short v162, v138, s[100:101] offset:-4096 nt
	v_lshlrev_b32_e32 v139, 16, v139
	v_mul_f32_e32 v139, 0x3fb504f3, v139
	v_fma_mixlo_f16 v139, s36, v38, v139
	global_store_short v162, v139, s[100:101] offset:-4032 nt
	v_lshlrev_b32_e32 v140, 16, v140
	v_mul_f32_e32 v140, 0x3fb504f3, v140
	v_fma_mixlo_f16 v140, s36, v55, v140
	global_store_short v162, v140, s[100:101] offset:-2048 nt
	v_lshlrev_b32_e32 v141, 16, v141
	v_mul_f32_e32 v141, 0x3fb504f3, v141
	v_fma_mixlo_f16 v141, s36, v39, v141
	global_store_short v162, v141, s[100:101] offset:-1984 nt
	v_lshlrev_b32_e32 v142, 16, v142
	v_mul_f32_e32 v142, 0x3fb504f3, v142
	v_fma_mixlo_f16 v142, s36, v56, v142
	global_store_short v162, v142, s[100:101] offset:0 nt
	v_lshlrev_b32_e32 v143, 16, v143
	v_mul_f32_e32 v143, 0x3fb504f3, v143
	v_fma_mixlo_f16 v143, s36, v40, v143
	global_store_short v162, v143, s[100:101] offset:64 nt
	v_lshlrev_b32_e32 v144, 16, v144
	v_mul_f32_e32 v144, 0x3fb504f3, v144
	v_fma_mixlo_f16 v144, s36, v57, v144
	global_store_short v162, v144, s[100:101] offset:2048 nt
	v_lshlrev_b32_e32 v145, 16, v145
	v_mul_f32_e32 v145, 0x3fb504f3, v145
	v_fma_mixlo_f16 v145, s36, v41, v145
	global_store_short v162, v145, s[100:101] offset:2112 nt
	s_add_u32 s100, s100, 0x4000
	s_addc_u32 s101, s101, 0
	global_load_ushort v130, v162, s[98:99] offset:-4096 nt
	global_load_ushort v131, v162, s[98:99] offset:-4032 nt
	global_load_ushort v132, v162, s[98:99] offset:-2048 nt
	global_load_ushort v133, v162, s[98:99] offset:-1984 nt
	global_load_ushort v134, v162, s[98:99] offset:0 nt
	global_load_ushort v135, v162, s[98:99] offset:64 nt
	global_load_ushort v136, v162, s[98:99] offset:2048 nt
	global_load_ushort v137, v162, s[98:99] offset:2112 nt
	s_add_u32 s98, s98, 0x4000
	s_addc_u32 s99, s99, 0
	global_load_ushort v138, v162, s[98:99] offset:-4096 nt
	global_load_ushort v139, v162, s[98:99] offset:-4032 nt
	global_load_ushort v140, v162, s[98:99] offset:-2048 nt
	global_load_ushort v141, v162, s[98:99] offset:-1984 nt
	global_load_ushort v142, v162, s[98:99] offset:0 nt
	global_load_ushort v143, v162, s[98:99] offset:64 nt
	global_load_ushort v144, v162, s[98:99] offset:2048 nt
	global_load_ushort v145, v162, s[98:99] offset:2112 nt
	s_add_u32 s98, s98, 0x4000
	s_addc_u32 s99, s99, 0
	s_waitcnt vmcnt(32)
; DI float bf2f(u16 v) { return __uint_as_float(((unsigned)v) << 16); }
; DI int crow(int i, int h) { return (i & 3) + 8 * (i >> 2) + 4 * h; }
; DI void phase_gemm_resid(const Params& p, const u16* A, int lda, int K, const u16* Bt, bool last_sub, float scl,
;                          int row0, int nrows, char* smem) {
;     ...
;         for (int i = 0; i < 16; ++i) {
;           const size_t row = (size_t)row0 + mt * 256 + wm * 128 + ms * 32 + crow(i, lh);
;           const int col = nt * 256 + wn * 64 + ns * 32 + lr;
;           __builtin_nontemporal_store(__builtin_bit_cast(u16, (_Float16)(ALPHA * bf2f(xres[row * D + col]) + scl * acc[ms][ns][i])), &r16[row * D + col]);
;         }
	v_lshlrev_b32_e32 v146, 16, v146
	v_mul_f32_e32 v146, 0x3fb504f3, v146
	v_fma_mixlo_f16 v146, s36, v58, v146
	global_store_short v162, v146, s[100:101] offset:-4096 nt
	v_lshlrev_b32_e32 v147, 16, v147
	v_mul_f32_e32 v147, 0x3fb504f3, v147
	v_fma_mixlo_f16 v147, s36, v42, v147
	global_store_short v162, v147, s[100:101] offset:-4032 nt
	v_lshlrev_b32_e32 v148, 16, v148
	v_mul_f32_e32 v148, 0x3fb504f3, v148
	v_fma_mixlo_f16 v148, s36, v59, v148
	global_store_short v162, v148, s[100:101] offset:-2048 nt
	v_lshlrev_b32_e32 v149, 16, v149
	v_mul_f32_e32 v149, 0x3fb504f3, v149
	v_fma_mixlo_f16 v149, s36, v43, v149
	global_store_short v162, v149, s[100:101] offset:-1984 nt
	v_lshlrev_b32_e32 v150, 16, v150
	v_mul_f32_e32 v150, 0x3fb504f3, v150
	v_fma_mixlo_f16 v150, s36, v60, v150
	global_store_short v162, v150, s[100:101] offset:0 nt
	v_lshlrev_b32_e32 v151, 16, v151
	v_mul_f32_e32 v151, 0x3fb504f3, v151
	v_fma_mixlo_f16 v151, s36, v44, v151
	global_store_short v162, v151, s[100:101] offset:64 nt
	v_lshlrev_b32_e32 v152, 16, v152
	v_mul_f32_e32 v152, 0x3fb504f3, v152
	v_fma_mixlo_f16 v152, s36, v61, v152
	global_store_short v162, v152, s[100:101] offset:2048 nt
	v_lshlrev_b32_e32 v153, 16, v153
	v_mul_f32_e32 v153, 0x3fb504f3, v153
	v_fma_mixlo_f16 v153, s36, v45, v153
	global_store_short v162, v153, s[100:101] offset:2112 nt
	s_add_u32 s100, s100, 0x4000
	s_addc_u32 s101, s101, 0
	v_lshlrev_b32_e32 v154, 16, v154
	v_mul_f32_e32 v154, 0x3fb504f3, v154
	v_fma_mixlo_f16 v154, s36, v62, v154
	global_store_short v162, v154, s[100:101] offset:-4096 nt
	v_lshlrev_b32_e32 v155, 16, v155
	v_mul_f32_e32 v155, 0x3fb504f3, v155
	v_fma_mixlo_f16 v155, s36, v46, v155
	global_store_short v162, v155, s[100:101] offset:-4032 nt
	v_lshlrev_b32_e32 v156, 16, v156
	v_mul_f32_e32 v156, 0x3fb504f3, v156
	v_fma_mixlo_f16 v156, s36, v63, v156
	global_store_short v162, v156, s[100:101] offset:-2048 nt
	v_lshlrev_b32_e32 v157, 16, v157
	v_mul_f32_e32 v157, 0x3fb504f3, v157
	v_fma_mixlo_f16 v157, s36, v47, v157
	global_store_short v162, v157, s[100:101] offset:-1984 nt
	v_lshlrev_b32_e32 v158, 16, v158
	v_mul_f32_e32 v158, 0x3fb504f3, v158
	v_fma_mixlo_f16 v158, s36, v64, v158
	global_store_short v162, v158, s[100:101] offset:0 nt
	v_lshlrev_b32_e32 v159, 16, v159
	v_mul_f32_e32 v159, 0x3fb504f3, v159
	v_fma_mixlo_f16 v159, s36, v48, v159
	global_store_short v162, v159, s[100:101] offset:64 nt
	v_lshlrev_b32_e32 v160, 16, v160
	v_mul_f32_e32 v160, 0x3fb504f3, v160
	v_fma_mixlo_f16 v160, s36, v65, v160
	global_store_short v162, v160, s[100:101] offset:2048 nt
	v_lshlrev_b32_e32 v161, 16, v161
	v_mul_f32_e32 v161, 0x3fb504f3, v161
	v_fma_mixlo_f16 v161, s36, v49, v161
	global_store_short v162, v161, s[100:101] offset:2112 nt
	s_add_u32 s100, s100, 0x4000
	s_addc_u32 s101, s101, 0
	global_load_ushort v146, v162, s[98:99] offset:-4096 nt
	global_load_ushort v147, v162, s[98:99] offset:-4032 nt
	global_load_ushort v148, v162, s[98:99] offset:-2048 nt
	global_load_ushort v149, v162, s[98:99] offset:-1984 nt
	global_load_ushort v150, v162, s[98:99] offset:0 nt
	global_load_ushort v151, v162, s[98:99] offset:64 nt
	global_load_ushort v152, v162, s[98:99] offset:2048 nt
	global_load_ushort v153, v162, s[98:99] offset:2112 nt
	s_add_u32 s98, s98, 0x4000
	s_addc_u32 s99, s99, 0
	global_load_ushort v154, v162, s[98:99] offset:-4096 nt
	global_load_ushort v155, v162, s[98:99] offset:-4032 nt
	global_load_ushort v156, v162, s[98:99] offset:-2048 nt
	global_load_ushort v157, v162, s[98:99] offset:-1984 nt
	global_load_ushort v158, v162, s[98:99] offset:0 nt
	global_load_ushort v159, v162, s[98:99] offset:64 nt
	global_load_ushort v160, v162, s[98:99] offset:2048 nt
	global_load_ushort v161, v162, s[98:99] offset:2112 nt
	s_add_u32 s98, s98, 0x4000
	s_addc_u32 s99, s99, 0
	s_waitcnt vmcnt(32)
; DI float bf2f(u16 v) { return __uint_as_float(((unsigned)v) << 16); }
; DI int crow(int i, int h) { return (i & 3) + 8 * (i >> 2) + 4 * h; }
; template <class Toff, class Setup, class Epi>
; DI void gemm256_stream(int tiles_per_xcd, int K, long ais, long akcs, long bis, Toff toff, Setup setup, Epi epi, char* smem) {
;     ...
;     if (!has_next) break;
;     q = qn;
;     Ac = An;
;     Bc = Bn;
;     G256_GLOAD(Ac, Bc, 1)
; DI void phase_gemm_resid(const Params& p, const u16* A, int lda, int K, const u16* Bt, bool last_sub, float scl,
;                          int row0, int nrows, char* smem) {
;     ...
;         for (int i = 0; i < 16; ++i) {
;           const size_t row = (size_t)row0 + mt * 256 + wm * 128 + ms * 32 + crow(i, lh);
;           const int col = nt * 256 + wn * 64 + ns * 32 + lr;
;           __builtin_nontemporal_store(__builtin_bit_cast(u16, (_Float16)(ALPHA * bf2f(xres[row * D + col]) + scl * acc[ms][ns][i])), &r16[row * D + col]);
;         }
;   };
	v_lshlrev_b32_e32 v130, 16, v130
	v_mul_f32_e32 v130, 0x3fb504f3, v130
	v_fma_mixlo_f16 v130, s36, v18, v130
	global_store_short v162, v130, s[100:101] offset:-4096 nt
	v_lshlrev_b32_e32 v131, 16, v131
	v_mul_f32_e32 v131, 0x3fb504f3, v131
	v_fma_mixlo_f16 v131, s36, v2, v131
	global_store_short v162, v131, s[100:101] offset:-4032 nt
	v_lshlrev_b32_e32 v132, 16, v132
	v_mul_f32_e32 v132, 0x3fb504f3, v132
	v_fma_mixlo_f16 v132, s36, v19, v132
	global_store_short v162, v132, s[100:101] offset:-2048 nt
	v_lshlrev_b32_e32 v133, 16, v133
	v_mul_f32_e32 v133, 0x3fb504f3, v133
	v_fma_mixlo_f16 v133, s36, v3, v133
	global_store_short v162, v133, s[100:101] offset:-1984 nt
	v_lshlrev_b32_e32 v134, 16, v134
	v_mul_f32_e32 v134, 0x3fb504f3, v134
	v_fma_mixlo_f16 v134, s36, v20, v134
	global_store_short v162, v134, s[100:101] offset:0 nt
	v_lshlrev_b32_e32 v135, 16, v135
	v_mul_f32_e32 v135, 0x3fb504f3, v135
	v_fma_mixlo_f16 v135, s36, v4, v135
	global_store_short v162, v135, s[100:101] offset:64 nt
	v_lshlrev_b32_e32 v136, 16, v136
	v_mul_f32_e32 v136, 0x3fb504f3, v136
	v_fma_mixlo_f16 v136, s36, v21, v136
	global_store_short v162, v136, s[100:101] offset:2048 nt
	v_lshlrev_b32_e32 v137, 16, v137
	v_mul_f32_e32 v137, 0x3fb504f3, v137
	v_fma_mixlo_f16 v137, s36, v5, v137
	global_store_short v162, v137, s[100:101] offset:2112 nt
	s_add_u32 s100, s100, 0x4000
	s_addc_u32 s101, s101, 0
	v_lshlrev_b32_e32 v138, 16, v138
	v_mul_f32_e32 v138, 0x3fb504f3, v138
	v_fma_mixlo_f16 v138, s36, v22, v138
	global_store_short v162, v138, s[100:101] offset:-4096 nt
	v_lshlrev_b32_e32 v139, 16, v139
	v_mul_f32_e32 v139, 0x3fb504f3, v139
	v_fma_mixlo_f16 v139, s36, v6, v139
	global_store_short v162, v139, s[100:101] offset:-4032 nt
	v_lshlrev_b32_e32 v140, 16, v140
	v_mul_f32_e32 v140, 0x3fb504f3, v140
	v_fma_mixlo_f16 v140, s36, v23, v140
	global_store_short v162, v140, s[100:101] offset:-2048 nt
	v_lshlrev_b32_e32 v141, 16, v141
	v_mul_f32_e32 v141, 0x3fb504f3, v141
	v_fma_mixlo_f16 v141, s36, v7, v141
	global_store_short v162, v141, s[100:101] offset:-1984 nt
	v_lshlrev_b32_e32 v142, 16, v142
	v_mul_f32_e32 v142, 0x3fb504f3, v142
	v_fma_mixlo_f16 v142, s36, v24, v142
	global_store_short v162, v142, s[100:101] offset:0 nt
	v_lshlrev_b32_e32 v143, 16, v143
	v_mul_f32_e32 v143, 0x3fb504f3, v143
	v_fma_mixlo_f16 v143, s36, v8, v143
	global_store_short v162, v143, s[100:101] offset:64 nt
	v_lshlrev_b32_e32 v144, 16, v144
	v_mul_f32_e32 v144, 0x3fb504f3, v144
	v_fma_mixlo_f16 v144, s36, v25, v144
	global_store_short v162, v144, s[100:101] offset:2048 nt
	v_lshlrev_b32_e32 v145, 16, v145
	v_mul_f32_e32 v145, 0x3fb504f3, v145
	v_fma_mixlo_f16 v145, s36, v9, v145
	global_store_short v162, v145, s[100:101] offset:2112 nt
	s_add_u32 s100, s100, 0x4000
	s_addc_u32 s101, s101, 0
	s_waitcnt vmcnt(16)
	v_lshlrev_b32_e32 v146, 16, v146
	v_mul_f32_e32 v146, 0x3fb504f3, v146
	v_fma_mixlo_f16 v146, s36, v26, v146
	global_store_short v162, v146, s[100:101] offset:-4096 nt
	v_lshlrev_b32_e32 v147, 16, v147
	v_mul_f32_e32 v147, 0x3fb504f3, v147
	v_fma_mixlo_f16 v147, s36, v10, v147
	global_store_short v162, v147, s[100:101] offset:-4032 nt
	v_lshlrev_b32_e32 v148, 16, v148
	v_mul_f32_e32 v148, 0x3fb504f3, v148
	v_fma_mixlo_f16 v148, s36, v27, v148
	global_store_short v162, v148, s[100:101] offset:-2048 nt
	v_lshlrev_b32_e32 v149, 16, v149
	v_mul_f32_e32 v149, 0x3fb504f3, v149
	v_fma_mixlo_f16 v149, s36, v11, v149
	global_store_short v162, v149, s[100:101] offset:-1984 nt
	v_lshlrev_b32_e32 v150, 16, v150
	v_mul_f32_e32 v150, 0x3fb504f3, v150
	v_fma_mixlo_f16 v150, s36, v28, v150
	global_store_short v162, v150, s[100:101] offset:0 nt
	v_lshlrev_b32_e32 v151, 16, v151
	v_mul_f32_e32 v151, 0x3fb504f3, v151
	v_fma_mixlo_f16 v151, s36, v12, v151
	global_store_short v162, v151, s[100:101] offset:64 nt
	v_lshlrev_b32_e32 v152, 16, v152
	v_mul_f32_e32 v152, 0x3fb504f3, v152
	v_fma_mixlo_f16 v152, s36, v29, v152
	global_store_short v162, v152, s[100:101] offset:2048 nt
	v_lshlrev_b32_e32 v153, 16, v153
	v_mul_f32_e32 v153, 0x3fb504f3, v153
	v_fma_mixlo_f16 v153, s36, v13, v153
	global_store_short v162, v153, s[100:101] offset:2112 nt
	s_add_u32 s100, s100, 0x4000
	s_addc_u32 s101, s101, 0
	v_lshlrev_b32_e32 v154, 16, v154
	v_mul_f32_e32 v154, 0x3fb504f3, v154
	v_fma_mixlo_f16 v154, s36, v30, v154
	global_store_short v162, v154, s[100:101] offset:-4096 nt
	v_lshlrev_b32_e32 v155, 16, v155
	v_mul_f32_e32 v155, 0x3fb504f3, v155
	v_fma_mixlo_f16 v155, s36, v14, v155
	global_store_short v162, v155, s[100:101] offset:-4032 nt
	v_lshlrev_b32_e32 v156, 16, v156
	v_mul_f32_e32 v156, 0x3fb504f3, v156
	v_fma_mixlo_f16 v156, s36, v31, v156
	global_store_short v162, v156, s[100:101] offset:-2048 nt
	v_lshlrev_b32_e32 v157, 16, v157
	v_mul_f32_e32 v157, 0x3fb504f3, v157
	v_fma_mixlo_f16 v157, s36, v15, v157
	global_store_short v162, v157, s[100:101] offset:-1984 nt
	v_lshlrev_b32_e32 v158, 16, v158
	v_mul_f32_e32 v158, 0x3fb504f3, v158
	v_fma_mixlo_f16 v158, s36, v32, v158
	global_store_short v162, v158, s[100:101] offset:0 nt
	v_lshlrev_b32_e32 v159, 16, v159
	v_mul_f32_e32 v159, 0x3fb504f3, v159
	v_fma_mixlo_f16 v159, s36, v16, v159
	global_store_short v162, v159, s[100:101] offset:64 nt
	v_lshlrev_b32_e32 v160, 16, v160
	v_mul_f32_e32 v160, 0x3fb504f3, v160
	v_fma_mixlo_f16 v160, s36, v33, v160
	global_store_short v162, v160, s[100:101] offset:2048 nt
	v_lshlrev_b32_e32 v161, 16, v161
	v_mul_f32_e32 v161, 0x3fb504f3, v161
	v_fma_mixlo_f16 v161, s36, v17, v161
	global_store_short v162, v161, s[100:101] offset:2112 nt
	s_add_u32 s100, s100, 0x4000
	s_addc_u32 s101, s101, 0
	s_cbranch_vccz .LBB0_821
	s_lshl_b64 s[0:1], s[76:77], 1
	v_lshl_add_u64 v[2:3], v[190:191], 0, s[0:1]
	v_lshl_add_u64 v[4:5], v[188:189], 0, s[0:1]
	global_load_dwordx4 v[146:149], v[190:191], off offset:128
	global_load_dwordx4 v[158:161], v[188:189], off offset:128
	global_load_dwordx4 v[138:141], v[2:3], off offset:128
	global_load_dwordx4 v[154:157], v[4:5], off offset:128
	v_lshl_add_u64 v[2:3], v[2:3], 0, s[78:79]
	v_lshl_add_u64 v[4:5], v[4:5], 0, s[78:79]
	global_load_dwordx4 v[134:137], v[2:3], off offset:128
	global_load_dwordx4 v[150:153], v[4:5], off offset:128
	v_lshl_add_u64 v[2:3], v[2:3], 0, s[78:79]
	v_lshl_add_u64 v[4:5], v[4:5], 0, s[78:79]
	global_load_dwordx4 v[130:133], v[2:3], off offset:128
	global_load_dwordx4 v[142:145], v[4:5], off offset:128
	s_mov_b64 s[8:9], 0
	s_branch .LBB0_821
